# cmlp item loop hand-rewritten: all loads of item k+1 prefetched during item k, counted waits, 2 barriers/item; cmlp items rebalanced 2/4 (P3) 0/4 (P5)
# speedup vs baseline: 1.0183x; 1.0183x over previous
.LBB0_682:
	s_mul_i32 s5, s2, 2
	s_add_i32 s5, s5, 0
	s_mov_b32 s3, 2
	s_cmpk_lt_i32 s2, 0x80
	s_cbranch_scc1 .Lcma_hd
	s_mul_i32 s5, s2, 4
	s_add_i32 s5, s5, -256
	s_mov_b32 s3, 4
.Lcma_hd:
	s_add_u32 s8, s30, 0x800000
	s_addc_u32 s9, s31, 0
	s_mov_b32 s4, 0x3a800000
	v_readlane_b32 s36, v254, 21
	v_readlane_b32 s37, v254, 22
	v_readlane_b32 s38, v254, 19
	v_readlane_b32 s39, v254, 20
	v_readlane_b32 s40, v254, 25
	v_readlane_b32 s41, v254, 26
	v_readlane_b32 s42, v254, 41
	v_readlane_b32 s43, v254, 42
	v_readlane_b32 s44, v254, 43
	v_readlane_b32 s45, v254, 44
	v_readlane_b32 s96, v254, 45
	v_readlane_b32 s97, v254, 46
	v_and_b32_e32 v1, 15, v195
	v_lshrrev_b32_e32 v0, 4, v195
	v_lshlrev_b32_e32 v2, 4, v1
	v_lshl_add_u32 v200, v0, 11, v2
	v_add_u32_e32 v201, 0x10000, v200
	v_add_u32_e32 v202, 0x20000, v200
	v_add_u32_e32 v203, 0x30000, v200
	v_lshl_add_u32 v204, v0, 8, v2
	v_add_u32_e32 v205, 0x2000, v204
	v_add_u32_e32 v206, 0x4000, v204
	v_add_u32_e32 v207, 0x6000, v204
	v_and_b32_e32 v3, 0x7f, v195
	v_lshlrev_b32_e32 v208, 7, v3
	v_lshlrev_b32_e32 v209, 5, v1
	v_lshrrev_b32_e32 v4, 6, v195
	v_lshl_add_u32 v5, v4, 4, v1
	v_lshlrev_b32_e32 v210, 2, v5
	v_bfe_u32 v6, v195, 4, 2
	v_lshlrev_b32_e32 v7, 3, v6
	v_lshl_add_u32 v211, v5, 11, v7
	v_mul_u32_u24_e32 v8, 0x120, v0
	v_add_u32_e32 v212, v8, v2
	v_mul_u32_u24_e32 v8, 0x110, v0
	v_add_u32_e32 v8, v8, v2
	v_add_u32_e32 v213, 0x9000, v8
	v_lshlrev_b32_e32 v8, 3, v0
	v_add_u32_e32 v214, 0x11800, v8
	v_lshlrev_b32_e32 v8, 3, v195
	v_add_u32_e32 v215, 0x11800, v8
	v_lshrrev_b32_e32 v8, 2, v1
	v_lshl_or_b32 v8, v6, 2, v8
	v_mul_u32_u24_e32 v8, 0x120, v8
	v_and_b32_e32 v9, 3, v195
	v_lshl_add_u32 v216, v9, 3, v8
	v_mul_u32_u24_e32 v8, 0x110, v5
	v_add_u32_e32 v8, v8, v7
	v_add_u32_e32 v217, 0x9000, v8
	s_mov_b32 s0, s5
	s_and_b32 s1, s0, 7
	s_lshr_b32 s0, s0, 3
	s_lshl_b32 s0, s0, 7
	s_lshl_b32 s10, s1, 8
	s_lshl_b32 s11, s0, 11
	s_add_u32 s11, s11, s10
	s_add_u32 s46, s42, s11
	s_addc_u32 s47, s43, 0
	s_add_u32 s6, s96, s11
	s_addc_u32 s7, s97, 0
	s_lshl_b32 s10, s1, 15
	s_add_u32 s48, s8, s10
	s_addc_u32 s49, s9, 0
	s_lshl_b32 s10, s0, 7
	s_add_u32 s50, s44, s10
	s_addc_u32 s51, s45, 0
	s_lshl_b32 s10, s1, 9
	s_add_u32 s14, s36, s10
	s_addc_u32 s15, s37, 0
	s_add_u32 s16, s38, s10
	s_addc_u32 s17, s39, 0
	s_add_u32 s10, s40, s10
	s_addc_u32 s11, s41, 0
	v_readfirstlane_b32 s0, v195
	s_nop 1
	s_cmp_lt_u32 s0, 0x80
	s_cbranch_scc0 .Lcma_pf0
	global_load_dwordx4 v[132:135], v208, s[50:51]
	global_load_dwordx4 v[136:139], v208, s[50:51] offset:16
	global_load_dwordx4 v[140:143], v208, s[50:51] offset:32
	global_load_dwordx4 v[144:147], v208, s[50:51] offset:48
	global_load_dwordx4 v[148:151], v208, s[50:51] offset:64
	global_load_dwordx4 v[152:155], v208, s[50:51] offset:80
	global_load_dwordx4 v[156:159], v208, s[50:51] offset:96
	global_load_dwordx4 v[160:163], v208, s[50:51] offset:112
.Lcma_pf0:
	global_load_dwordx4 v[100:103], v200, s[46:47]
	global_load_dwordx4 v[116:119], v204, s[48:49]
	global_load_dwordx4 v[104:107], v201, s[46:47]
	global_load_dwordx4 v[120:123], v205, s[48:49]
	global_load_dwordx4 v[108:111], v202, s[46:47]
	global_load_dwordx4 v[124:127], v206, s[48:49]
	global_load_dwordx4 v[112:115], v203, s[46:47]
	global_load_dwordx4 v[128:131], v207, s[48:49]
	global_load_dwordx4 v[164:167], v209, s[14:15]
	global_load_dwordx4 v[168:171], v209, s[16:17]
	global_load_dwordx4 v[172:175], v209, s[16:17] offset:16
	global_load_dwordx4 v[176:179], v209, s[14:15] offset:16
	global_load_dword v236, v210, s[10:11]
	global_load_dwordx2 v[220:221], v211, s[6:7]
	global_load_dwordx2 v[222:223], v211, s[6:7] offset:32
	global_load_dwordx2 v[224:225], v211, s[6:7] offset:64
	global_load_dwordx2 v[226:227], v211, s[6:7] offset:96
	global_load_dwordx2 v[228:229], v211, s[6:7] offset:128
	global_load_dwordx2 v[230:231], v211, s[6:7] offset:160
	global_load_dwordx2 v[232:233], v211, s[6:7] offset:192
	global_load_dwordx2 v[234:235], v211, s[6:7] offset:224
	s_waitcnt vmcnt(0)
	s_branch .Lcma_copy
.Lcma_top:
	s_waitcnt vmcnt(8)
.Lcma_copy:
	s_mov_b64 s[12:13], s[6:7]
	v_mov_b32_e32 v0, v100
	v_mov_b32_e32 v1, v101
	v_mov_b32_e32 v2, v102
	v_mov_b32_e32 v3, v103
	v_mov_b32_e32 v4, v104
	v_mov_b32_e32 v5, v105
	v_mov_b32_e32 v6, v106
	v_mov_b32_e32 v7, v107
	v_mov_b32_e32 v8, v108
	v_mov_b32_e32 v9, v109
	v_mov_b32_e32 v10, v110
	v_mov_b32_e32 v11, v111
	v_mov_b32_e32 v12, v112
	v_mov_b32_e32 v13, v113
	v_mov_b32_e32 v14, v114
	v_mov_b32_e32 v15, v115
	v_mov_b32_e32 v16, v116
	v_mov_b32_e32 v17, v117
	v_mov_b32_e32 v18, v118
	v_mov_b32_e32 v19, v119
	v_mov_b32_e32 v20, v120
	v_mov_b32_e32 v21, v121
	v_mov_b32_e32 v22, v122
	v_mov_b32_e32 v23, v123
	v_mov_b32_e32 v24, v124
	v_mov_b32_e32 v25, v125
	v_mov_b32_e32 v26, v126
	v_mov_b32_e32 v27, v127
	v_mov_b32_e32 v28, v128
	v_mov_b32_e32 v29, v129
	v_mov_b32_e32 v30, v130
	v_mov_b32_e32 v31, v131
	v_mov_b32_e32 v38, v164
	v_mov_b32_e32 v39, v165
	v_mov_b32_e32 v40, v166
	v_mov_b32_e32 v41, v167
	v_mov_b32_e32 v42, v168
	v_mov_b32_e32 v43, v169
	v_mov_b32_e32 v44, v170
	v_mov_b32_e32 v45, v171
	v_mov_b32_e32 v46, v172
	v_mov_b32_e32 v47, v173
	v_mov_b32_e32 v48, v174
	v_mov_b32_e32 v49, v175
	v_mov_b32_e32 v50, v176
	v_mov_b32_e32 v51, v177
	v_mov_b32_e32 v52, v178
	v_mov_b32_e32 v53, v179
	v_mov_b32_e32 v70, v220
	v_mov_b32_e32 v71, v221
	v_mov_b32_e32 v72, v222
	v_mov_b32_e32 v73, v223
	v_mov_b32_e32 v74, v224
	v_mov_b32_e32 v75, v225
	v_mov_b32_e32 v76, v226
	v_mov_b32_e32 v77, v227
	v_mov_b32_e32 v78, v228
	v_mov_b32_e32 v79, v229
	v_mov_b32_e32 v80, v230
	v_mov_b32_e32 v81, v231
	v_mov_b32_e32 v82, v232
	v_mov_b32_e32 v83, v233
	v_mov_b32_e32 v84, v234
	v_mov_b32_e32 v85, v235
	v_mov_b32_e32 v86, v236
	v_readfirstlane_b32 s0, v195
	s_nop 1
	s_cmp_lt_u32 s0, 0x80
	s_cbranch_scc0 .Lcma_nostat
	v_pk_add_f32 v[56:57], v[132:133], v[134:135]
	v_pk_add_f32 v[60:61], v[136:137], v[138:139]
	v_pk_add_f32 v[56:57], v[56:57], 0 op_sel_hi:[1,0]
	v_pk_add_f32 v[58:59], v[140:141], v[142:143]
	v_pk_add_f32 v[56:57], v[56:57], v[60:61]
	v_pk_add_f32 v[60:61], v[144:145], v[146:147]
	v_pk_add_f32 v[56:57], v[56:57], v[58:59]
	v_pk_add_f32 v[58:59], v[148:149], v[150:151]
	v_pk_add_f32 v[56:57], v[56:57], v[60:61]
	v_pk_add_f32 v[60:61], v[152:153], v[154:155]
	v_pk_add_f32 v[56:57], v[56:57], v[58:59]
	v_pk_add_f32 v[58:59], v[156:157], v[158:159]
	v_pk_add_f32 v[56:57], v[56:57], v[60:61]
	v_pk_add_f32 v[60:61], v[160:161], v[162:163]
	v_pk_add_f32 v[56:57], v[56:57], v[58:59]
	s_nop 0
	v_pk_add_f32 v[56:57], v[56:57], v[60:61]
	s_nop 0
	v_pk_mul_f32 v[56:57], v[56:57], s[4:5] op_sel_hi:[1,0]
	s_nop 0
	v_fma_f32 v58, -v56, v56, v57
	v_max_f32_e32 v58, 0, v58
	v_add_f32_e32 v58, 0x358637bd, v58
	v_rsq_f32_e32 v57, v58
	s_nop 1
	ds_write_b64 v215, v[56:57]
.Lcma_nostat:
	s_cmp_gt_u32 s3, 1
	s_cbranch_scc0 .Lcma_nopf
	s_add_i32 s0, s5, 1
	s_and_b32 s1, s0, 7
	s_lshr_b32 s0, s0, 3
	s_lshl_b32 s0, s0, 7
	s_lshl_b32 s10, s1, 8
	s_lshl_b32 s11, s0, 11
	s_add_u32 s11, s11, s10
	s_add_u32 s46, s42, s11
	s_addc_u32 s47, s43, 0
	s_add_u32 s6, s96, s11
	s_addc_u32 s7, s97, 0
	s_lshl_b32 s10, s1, 15
	s_add_u32 s48, s8, s10
	s_addc_u32 s49, s9, 0
	s_lshl_b32 s10, s0, 7
	s_add_u32 s50, s44, s10
	s_addc_u32 s51, s45, 0
	s_lshl_b32 s10, s1, 9
	s_add_u32 s14, s36, s10
	s_addc_u32 s15, s37, 0
	s_add_u32 s16, s38, s10
	s_addc_u32 s17, s39, 0
	s_add_u32 s10, s40, s10
	s_addc_u32 s11, s41, 0
	v_readfirstlane_b32 s0, v195
	s_nop 1
	s_cmp_lt_u32 s0, 0x80
	s_cbranch_scc0 .Lcma_pf1
	global_load_dwordx4 v[132:135], v208, s[50:51]
	global_load_dwordx4 v[136:139], v208, s[50:51] offset:16
	global_load_dwordx4 v[140:143], v208, s[50:51] offset:32
	global_load_dwordx4 v[144:147], v208, s[50:51] offset:48
	global_load_dwordx4 v[148:151], v208, s[50:51] offset:64
	global_load_dwordx4 v[152:155], v208, s[50:51] offset:80
	global_load_dwordx4 v[156:159], v208, s[50:51] offset:96
	global_load_dwordx4 v[160:163], v208, s[50:51] offset:112
.Lcma_pf1:
	global_load_dwordx4 v[100:103], v200, s[46:47]
	global_load_dwordx4 v[116:119], v204, s[48:49]
	global_load_dwordx4 v[104:107], v201, s[46:47]
	global_load_dwordx4 v[120:123], v205, s[48:49]
	global_load_dwordx4 v[108:111], v202, s[46:47]
	global_load_dwordx4 v[124:127], v206, s[48:49]
	global_load_dwordx4 v[112:115], v203, s[46:47]
	global_load_dwordx4 v[128:131], v207, s[48:49]
	global_load_dwordx4 v[164:167], v209, s[14:15]
	global_load_dwordx4 v[168:171], v209, s[16:17]
	global_load_dwordx4 v[172:175], v209, s[16:17] offset:16
	global_load_dwordx4 v[176:179], v209, s[14:15] offset:16
	global_load_dword v236, v210, s[10:11]
	global_load_dwordx2 v[220:221], v211, s[6:7]
	global_load_dwordx2 v[222:223], v211, s[6:7] offset:32
	global_load_dwordx2 v[224:225], v211, s[6:7] offset:64
	global_load_dwordx2 v[226:227], v211, s[6:7] offset:96
	global_load_dwordx2 v[228:229], v211, s[6:7] offset:128
	global_load_dwordx2 v[230:231], v211, s[6:7] offset:160
	global_load_dwordx2 v[232:233], v211, s[6:7] offset:192
	global_load_dwordx2 v[234:235], v211, s[6:7] offset:224
.Lcma_nopf:
	s_waitcnt lgkmcnt(0)
	s_barrier
	ds_read_b64 v[88:89], v214
	ds_read_b64 v[90:91], v214 offset:256
	ds_read_b64 v[92:93], v214 offset:512
	ds_read_b64 v[94:95], v214 offset:768
	s_waitcnt lgkmcnt(3)
	v_lshlrev_b32_e32 v56, 16, v0
	v_and_b32_e32 v57, 0xffff0000, v0
	v_lshlrev_b32_e32 v58, 16, v1
	v_and_b32_e32 v59, 0xffff0000, v1
	v_lshlrev_b32_e32 v60, 16, v2
	v_and_b32_e32 v61, 0xffff0000, v2
	v_lshlrev_b32_e32 v62, 16, v3
	v_and_b32_e32 v63, 0xffff0000, v3
	v_sub_f32_e32 v56, v56, v88
	v_sub_f32_e32 v57, v57, v88
	v_sub_f32_e32 v58, v58, v88
	v_sub_f32_e32 v59, v59, v88
	v_sub_f32_e32 v60, v60, v88
	v_sub_f32_e32 v61, v61, v88
	v_sub_f32_e32 v62, v62, v88
	v_sub_f32_e32 v63, v63, v88
	v_mul_f32_e32 v56, v89, v56
	v_mul_f32_e32 v57, v89, v57
	v_mul_f32_e32 v58, v89, v58
	v_mul_f32_e32 v59, v89, v59
	v_mul_f32_e32 v60, v89, v60
	v_mul_f32_e32 v61, v89, v61
	v_mul_f32_e32 v62, v89, v62
	v_mul_f32_e32 v63, v89, v63
	v_fma_f32 v56, v42, v56, v38
	v_fma_f32 v57, v43, v57, v39
	v_fma_f32 v58, v44, v58, v40
	v_fma_f32 v59, v45, v59, v41
	v_fma_f32 v60, v46, v60, v50
	v_fma_f32 v61, v47, v61, v51
	v_fma_f32 v62, v48, v62, v52
	v_fma_f32 v63, v49, v63, v53
	v_cvt_pk_bf16_f32 v64, v56, v57
	v_cvt_pk_bf16_f32 v65, v58, v59
	v_cvt_pk_bf16_f32 v66, v60, v61
	v_cvt_pk_bf16_f32 v67, v62, v63
	ds_write_b128 v212, v[64:67]
	ds_write_b128 v213, v[16:19]
	s_waitcnt lgkmcnt(4)
	v_lshlrev_b32_e32 v56, 16, v4
	v_and_b32_e32 v57, 0xffff0000, v4
	v_lshlrev_b32_e32 v58, 16, v5
	v_and_b32_e32 v59, 0xffff0000, v5
	v_lshlrev_b32_e32 v60, 16, v6
	v_and_b32_e32 v61, 0xffff0000, v6
	v_lshlrev_b32_e32 v62, 16, v7
	v_and_b32_e32 v63, 0xffff0000, v7
	v_sub_f32_e32 v56, v56, v90
	v_sub_f32_e32 v57, v57, v90
	v_sub_f32_e32 v58, v58, v90
	v_sub_f32_e32 v59, v59, v90
	v_sub_f32_e32 v60, v60, v90
	v_sub_f32_e32 v61, v61, v90
	v_sub_f32_e32 v62, v62, v90
	v_sub_f32_e32 v63, v63, v90
	v_mul_f32_e32 v56, v91, v56
	v_mul_f32_e32 v57, v91, v57
	v_mul_f32_e32 v58, v91, v58
	v_mul_f32_e32 v59, v91, v59
	v_mul_f32_e32 v60, v91, v60
	v_mul_f32_e32 v61, v91, v61
	v_mul_f32_e32 v62, v91, v62
	v_mul_f32_e32 v63, v91, v63
	v_fma_f32 v56, v42, v56, v38
	v_fma_f32 v57, v43, v57, v39
	v_fma_f32 v58, v44, v58, v40
	v_fma_f32 v59, v45, v59, v41
	v_fma_f32 v60, v46, v60, v50
	v_fma_f32 v61, v47, v61, v51
	v_fma_f32 v62, v48, v62, v52
	v_fma_f32 v63, v49, v63, v53
	v_cvt_pk_bf16_f32 v64, v56, v57
	v_cvt_pk_bf16_f32 v65, v58, v59
	v_cvt_pk_bf16_f32 v66, v60, v61
	v_cvt_pk_bf16_f32 v67, v62, v63
	ds_write_b128 v212, v[64:67] offset:9216
	ds_write_b128 v213, v[20:23] offset:8704
	s_waitcnt lgkmcnt(5)
	v_lshlrev_b32_e32 v56, 16, v8
	v_and_b32_e32 v57, 0xffff0000, v8
	v_lshlrev_b32_e32 v58, 16, v9
	v_and_b32_e32 v59, 0xffff0000, v9
	v_lshlrev_b32_e32 v60, 16, v10
	v_and_b32_e32 v61, 0xffff0000, v10
	v_lshlrev_b32_e32 v62, 16, v11
	v_and_b32_e32 v63, 0xffff0000, v11
	v_sub_f32_e32 v56, v56, v92
	v_sub_f32_e32 v57, v57, v92
	v_sub_f32_e32 v58, v58, v92
	v_sub_f32_e32 v59, v59, v92
	v_sub_f32_e32 v60, v60, v92
	v_sub_f32_e32 v61, v61, v92
	v_sub_f32_e32 v62, v62, v92
	v_sub_f32_e32 v63, v63, v92
	v_mul_f32_e32 v56, v93, v56
	v_mul_f32_e32 v57, v93, v57
	v_mul_f32_e32 v58, v93, v58
	v_mul_f32_e32 v59, v93, v59
	v_mul_f32_e32 v60, v93, v60
	v_mul_f32_e32 v61, v93, v61
	v_mul_f32_e32 v62, v93, v62
	v_mul_f32_e32 v63, v93, v63
	v_fma_f32 v56, v42, v56, v38
	v_fma_f32 v57, v43, v57, v39
	v_fma_f32 v58, v44, v58, v40
	v_fma_f32 v59, v45, v59, v41
	v_fma_f32 v60, v46, v60, v50
	v_fma_f32 v61, v47, v61, v51
	v_fma_f32 v62, v48, v62, v52
	v_fma_f32 v63, v49, v63, v53
	v_cvt_pk_bf16_f32 v64, v56, v57
	v_cvt_pk_bf16_f32 v65, v58, v59
	v_cvt_pk_bf16_f32 v66, v60, v61
	v_cvt_pk_bf16_f32 v67, v62, v63
	ds_write_b128 v212, v[64:67] offset:18432
	ds_write_b128 v213, v[24:27] offset:17408
	s_waitcnt lgkmcnt(6)
	v_lshlrev_b32_e32 v56, 16, v12
	v_and_b32_e32 v57, 0xffff0000, v12
	v_lshlrev_b32_e32 v58, 16, v13
	v_and_b32_e32 v59, 0xffff0000, v13
	v_lshlrev_b32_e32 v60, 16, v14
	v_and_b32_e32 v61, 0xffff0000, v14
	v_lshlrev_b32_e32 v62, 16, v15
	v_and_b32_e32 v63, 0xffff0000, v15
	v_sub_f32_e32 v56, v56, v94
	v_sub_f32_e32 v57, v57, v94
	v_sub_f32_e32 v58, v58, v94
	v_sub_f32_e32 v59, v59, v94
	v_sub_f32_e32 v60, v60, v94
	v_sub_f32_e32 v61, v61, v94
	v_sub_f32_e32 v62, v62, v94
	v_sub_f32_e32 v63, v63, v94
	v_mul_f32_e32 v56, v95, v56
	v_mul_f32_e32 v57, v95, v57
	v_mul_f32_e32 v58, v95, v58
	v_mul_f32_e32 v59, v95, v59
	v_mul_f32_e32 v60, v95, v60
	v_mul_f32_e32 v61, v95, v61
	v_mul_f32_e32 v62, v95, v62
	v_mul_f32_e32 v63, v95, v63
	v_fma_f32 v56, v42, v56, v38
	v_fma_f32 v57, v43, v57, v39
	v_fma_f32 v58, v44, v58, v40
	v_fma_f32 v59, v45, v59, v41
	v_fma_f32 v60, v46, v60, v50
	v_fma_f32 v61, v47, v61, v51
	v_fma_f32 v62, v48, v62, v52
	v_fma_f32 v63, v49, v63, v53
	v_cvt_pk_bf16_f32 v64, v56, v57
	v_cvt_pk_bf16_f32 v65, v58, v59
	v_cvt_pk_bf16_f32 v66, v60, v61
	v_cvt_pk_bf16_f32 v67, v62, v63
	ds_write_b128 v212, v[64:67] offset:27648
	ds_write_b128 v213, v[28:31] offset:26112
	s_waitcnt lgkmcnt(0)
	s_barrier
	ds_read2_b64 v[12:15], v217 offset1:4
	ds_read2_b64 v[8:11], v217 offset0:8 offset1:12
	ds_read2_b64 v[0:3], v217 offset0:16 offset1:20
	ds_read2_b64 v[4:7], v217 offset0:24 offset1:28
	ds_read_b64_tr_b16 v[18:19], v216
	ds_read_b64_tr_b16 v[20:21], v216 offset:4608
	ds_read_b64_tr_b16 v[22:23], v216 offset:9216
	ds_read_b64_tr_b16 v[24:25], v216 offset:13824
	s_waitcnt lgkmcnt(2)
	v_mfma_f32_16x16x32_bf16 v[18:21], v[18:21], v[12:15], 0
	s_waitcnt lgkmcnt(0)
	v_mfma_f32_16x16x32_bf16 v[18:21], v[22:25], v[8:11], v[18:21]
	ds_read_b64_tr_b16 v[22:23], v216 offset:18432
	ds_read_b64_tr_b16 v[24:25], v216 offset:23040
	ds_read_b64_tr_b16 v[26:27], v216 offset:27648
	ds_read_b64_tr_b16 v[28:29], v216 offset:32256
	s_waitcnt lgkmcnt(2)
	v_mfma_f32_16x16x32_bf16 v[18:21], v[22:25], v[0:3], v[18:21]
	s_waitcnt lgkmcnt(0)
	v_mfma_f32_16x16x32_bf16 v[18:21], v[26:29], v[4:7], v[18:21]
	v_lshlrev_b32_e32 v24, 16, v70
	v_and_b32_e32 v22, 0xffff0000, v70
	v_lshlrev_b32_e32 v25, 16, v71
	v_and_b32_e32 v23, 0xffff0000, v71
	s_nop 3
	v_add_f32_e32 v18, v86, v18
	v_add_f32_e32 v19, v86, v19
	v_add_f32_e32 v20, v86, v20
	v_add_f32_e32 v21, v86, v21
	v_mul_f32_e32 v18, v18, v24
	v_mul_f32_e32 v19, v19, v22
	v_mul_f32_e32 v20, v20, v25
	v_mul_f32_e32 v21, v21, v23
	v_cvt_pk_bf16_f32 v30, v18, v19
	v_cvt_pk_bf16_f32 v31, v20, v21
	ds_read_b64_tr_b16 v[18:19], v216 offset:32
	ds_read_b64_tr_b16 v[20:21], v216 offset:4640
	ds_read_b64_tr_b16 v[22:23], v216 offset:9248
	ds_read_b64_tr_b16 v[24:25], v216 offset:13856
	s_waitcnt lgkmcnt(2)
	v_mfma_f32_16x16x32_bf16 v[18:21], v[18:21], v[12:15], 0
	s_waitcnt lgkmcnt(0)
	v_mfma_f32_16x16x32_bf16 v[18:21], v[22:25], v[8:11], v[18:21]
	ds_read_b64_tr_b16 v[22:23], v216 offset:18464
	ds_read_b64_tr_b16 v[24:25], v216 offset:23072
	ds_read_b64_tr_b16 v[26:27], v216 offset:27680
	ds_read_b64_tr_b16 v[28:29], v216 offset:32288
	global_store_dwordx2 v211, v[30:31], s[12:13]
	s_waitcnt lgkmcnt(2)
	v_mfma_f32_16x16x32_bf16 v[18:21], v[22:25], v[0:3], v[18:21]
	s_waitcnt lgkmcnt(0)
	v_mfma_f32_16x16x32_bf16 v[18:21], v[26:29], v[4:7], v[18:21]
	v_lshlrev_b32_e32 v24, 16, v72
	v_and_b32_e32 v22, 0xffff0000, v72
	v_lshlrev_b32_e32 v25, 16, v73
	v_and_b32_e32 v23, 0xffff0000, v73
	s_nop 3
	v_add_f32_e32 v18, v86, v18
	v_add_f32_e32 v19, v86, v19
	v_add_f32_e32 v20, v86, v20
	v_add_f32_e32 v21, v86, v21
	v_mul_f32_e32 v18, v18, v24
	v_mul_f32_e32 v19, v19, v22
	v_mul_f32_e32 v20, v20, v25
	v_mul_f32_e32 v21, v21, v23
	v_cvt_pk_bf16_f32 v30, v18, v19
	v_cvt_pk_bf16_f32 v31, v20, v21
	ds_read_b64_tr_b16 v[18:19], v216 offset:64
	ds_read_b64_tr_b16 v[20:21], v216 offset:4672
	ds_read_b64_tr_b16 v[22:23], v216 offset:9280
	ds_read_b64_tr_b16 v[24:25], v216 offset:13888
	s_waitcnt lgkmcnt(2)
	v_mfma_f32_16x16x32_bf16 v[18:21], v[18:21], v[12:15], 0
	s_waitcnt lgkmcnt(0)
	v_mfma_f32_16x16x32_bf16 v[18:21], v[22:25], v[8:11], v[18:21]
	ds_read_b64_tr_b16 v[22:23], v216 offset:18496
	ds_read_b64_tr_b16 v[24:25], v216 offset:23104
	ds_read_b64_tr_b16 v[26:27], v216 offset:27712
	ds_read_b64_tr_b16 v[28:29], v216 offset:32320
	global_store_dwordx2 v211, v[30:31], s[12:13] offset:32
	s_waitcnt lgkmcnt(2)
	v_mfma_f32_16x16x32_bf16 v[18:21], v[22:25], v[0:3], v[18:21]
	s_waitcnt lgkmcnt(0)
	v_mfma_f32_16x16x32_bf16 v[18:21], v[26:29], v[4:7], v[18:21]
	v_lshlrev_b32_e32 v24, 16, v74
	v_and_b32_e32 v22, 0xffff0000, v74
	v_lshlrev_b32_e32 v25, 16, v75
	v_and_b32_e32 v23, 0xffff0000, v75
	s_nop 3
	v_add_f32_e32 v18, v86, v18
	v_add_f32_e32 v19, v86, v19
	v_add_f32_e32 v20, v86, v20
	v_add_f32_e32 v21, v86, v21
	v_mul_f32_e32 v18, v18, v24
	v_mul_f32_e32 v19, v19, v22
	v_mul_f32_e32 v20, v20, v25
	v_mul_f32_e32 v21, v21, v23
	v_cvt_pk_bf16_f32 v30, v18, v19
	v_cvt_pk_bf16_f32 v31, v20, v21
	ds_read_b64_tr_b16 v[18:19], v216 offset:96
	ds_read_b64_tr_b16 v[20:21], v216 offset:4704
	ds_read_b64_tr_b16 v[22:23], v216 offset:9312
	ds_read_b64_tr_b16 v[24:25], v216 offset:13920
	s_waitcnt lgkmcnt(2)
	v_mfma_f32_16x16x32_bf16 v[18:21], v[18:21], v[12:15], 0
	s_waitcnt lgkmcnt(0)
	v_mfma_f32_16x16x32_bf16 v[18:21], v[22:25], v[8:11], v[18:21]
	ds_read_b64_tr_b16 v[22:23], v216 offset:18528
	ds_read_b64_tr_b16 v[24:25], v216 offset:23136
	ds_read_b64_tr_b16 v[26:27], v216 offset:27744
	ds_read_b64_tr_b16 v[28:29], v216 offset:32352
	global_store_dwordx2 v211, v[30:31], s[12:13] offset:64
	s_waitcnt lgkmcnt(2)
	v_mfma_f32_16x16x32_bf16 v[18:21], v[22:25], v[0:3], v[18:21]
	s_waitcnt lgkmcnt(0)
	v_mfma_f32_16x16x32_bf16 v[18:21], v[26:29], v[4:7], v[18:21]
	v_lshlrev_b32_e32 v24, 16, v76
	v_and_b32_e32 v22, 0xffff0000, v76
	v_lshlrev_b32_e32 v25, 16, v77
	v_and_b32_e32 v23, 0xffff0000, v77
	s_nop 3
	v_add_f32_e32 v18, v86, v18
	v_add_f32_e32 v19, v86, v19
	v_add_f32_e32 v20, v86, v20
	v_add_f32_e32 v21, v86, v21
	v_mul_f32_e32 v18, v18, v24
	v_mul_f32_e32 v19, v19, v22
	v_mul_f32_e32 v20, v20, v25
	v_mul_f32_e32 v21, v21, v23
	v_cvt_pk_bf16_f32 v30, v18, v19
	v_cvt_pk_bf16_f32 v31, v20, v21
	ds_read_b64_tr_b16 v[18:19], v216 offset:128
	ds_read_b64_tr_b16 v[20:21], v216 offset:4736
	ds_read_b64_tr_b16 v[22:23], v216 offset:9344
	ds_read_b64_tr_b16 v[24:25], v216 offset:13952
	s_waitcnt lgkmcnt(2)
	v_mfma_f32_16x16x32_bf16 v[18:21], v[18:21], v[12:15], 0
	s_waitcnt lgkmcnt(0)
	v_mfma_f32_16x16x32_bf16 v[18:21], v[22:25], v[8:11], v[18:21]
	ds_read_b64_tr_b16 v[22:23], v216 offset:18560
	ds_read_b64_tr_b16 v[24:25], v216 offset:23168
	ds_read_b64_tr_b16 v[26:27], v216 offset:27776
	ds_read_b64_tr_b16 v[28:29], v216 offset:32384
	global_store_dwordx2 v211, v[30:31], s[12:13] offset:96
	s_waitcnt lgkmcnt(2)
	v_mfma_f32_16x16x32_bf16 v[18:21], v[22:25], v[0:3], v[18:21]
	s_waitcnt lgkmcnt(0)
	v_mfma_f32_16x16x32_bf16 v[18:21], v[26:29], v[4:7], v[18:21]
	v_lshlrev_b32_e32 v24, 16, v78
	v_and_b32_e32 v22, 0xffff0000, v78
	v_lshlrev_b32_e32 v25, 16, v79
	v_and_b32_e32 v23, 0xffff0000, v79
	s_nop 3
	v_add_f32_e32 v18, v86, v18
	v_add_f32_e32 v19, v86, v19
	v_add_f32_e32 v20, v86, v20
	v_add_f32_e32 v21, v86, v21
	v_mul_f32_e32 v18, v18, v24
	v_mul_f32_e32 v19, v19, v22
	v_mul_f32_e32 v20, v20, v25
	v_mul_f32_e32 v21, v21, v23
	v_cvt_pk_bf16_f32 v30, v18, v19
	v_cvt_pk_bf16_f32 v31, v20, v21
	ds_read_b64_tr_b16 v[18:19], v216 offset:160
	ds_read_b64_tr_b16 v[20:21], v216 offset:4768
	ds_read_b64_tr_b16 v[22:23], v216 offset:9376
	ds_read_b64_tr_b16 v[24:25], v216 offset:13984
	s_waitcnt lgkmcnt(2)
	v_mfma_f32_16x16x32_bf16 v[18:21], v[18:21], v[12:15], 0
	s_waitcnt lgkmcnt(0)
	v_mfma_f32_16x16x32_bf16 v[18:21], v[22:25], v[8:11], v[18:21]
	ds_read_b64_tr_b16 v[22:23], v216 offset:18592
	ds_read_b64_tr_b16 v[24:25], v216 offset:23200
	ds_read_b64_tr_b16 v[26:27], v216 offset:27808
	ds_read_b64_tr_b16 v[28:29], v216 offset:32416
	global_store_dwordx2 v211, v[30:31], s[12:13] offset:128
	s_waitcnt lgkmcnt(2)
	v_mfma_f32_16x16x32_bf16 v[18:21], v[22:25], v[0:3], v[18:21]
	s_waitcnt lgkmcnt(0)
	v_mfma_f32_16x16x32_bf16 v[18:21], v[26:29], v[4:7], v[18:21]
	v_lshlrev_b32_e32 v24, 16, v80
	v_and_b32_e32 v22, 0xffff0000, v80
	v_lshlrev_b32_e32 v25, 16, v81
	v_and_b32_e32 v23, 0xffff0000, v81
	s_nop 3
	v_add_f32_e32 v18, v86, v18
	v_add_f32_e32 v19, v86, v19
	v_add_f32_e32 v20, v86, v20
	v_add_f32_e32 v21, v86, v21
	v_mul_f32_e32 v18, v18, v24
	v_mul_f32_e32 v19, v19, v22
	v_mul_f32_e32 v20, v20, v25
	v_mul_f32_e32 v21, v21, v23
	v_cvt_pk_bf16_f32 v30, v18, v19
	v_cvt_pk_bf16_f32 v31, v20, v21
	ds_read_b64_tr_b16 v[18:19], v216 offset:192
	ds_read_b64_tr_b16 v[20:21], v216 offset:4800
	ds_read_b64_tr_b16 v[22:23], v216 offset:9408
	ds_read_b64_tr_b16 v[24:25], v216 offset:14016
	s_waitcnt lgkmcnt(2)
	v_mfma_f32_16x16x32_bf16 v[18:21], v[18:21], v[12:15], 0
	s_waitcnt lgkmcnt(0)
	v_mfma_f32_16x16x32_bf16 v[18:21], v[22:25], v[8:11], v[18:21]
	ds_read_b64_tr_b16 v[22:23], v216 offset:18624
	ds_read_b64_tr_b16 v[24:25], v216 offset:23232
	ds_read_b64_tr_b16 v[26:27], v216 offset:27840
	ds_read_b64_tr_b16 v[28:29], v216 offset:32448
	global_store_dwordx2 v211, v[30:31], s[12:13] offset:160
	s_waitcnt lgkmcnt(2)
	v_mfma_f32_16x16x32_bf16 v[18:21], v[22:25], v[0:3], v[18:21]
	s_waitcnt lgkmcnt(0)
	v_mfma_f32_16x16x32_bf16 v[18:21], v[26:29], v[4:7], v[18:21]
	v_lshlrev_b32_e32 v24, 16, v82
	v_and_b32_e32 v22, 0xffff0000, v82
	v_lshlrev_b32_e32 v25, 16, v83
	v_and_b32_e32 v23, 0xffff0000, v83
	s_nop 3
	v_add_f32_e32 v18, v86, v18
	v_add_f32_e32 v19, v86, v19
	v_add_f32_e32 v20, v86, v20
	v_add_f32_e32 v21, v86, v21
	v_mul_f32_e32 v18, v18, v24
	v_mul_f32_e32 v19, v19, v22
	v_mul_f32_e32 v20, v20, v25
	v_mul_f32_e32 v21, v21, v23
	v_cvt_pk_bf16_f32 v30, v18, v19
	v_cvt_pk_bf16_f32 v31, v20, v21
	ds_read_b64_tr_b16 v[18:19], v216 offset:224
	ds_read_b64_tr_b16 v[20:21], v216 offset:4832
	ds_read_b64_tr_b16 v[22:23], v216 offset:9440
	ds_read_b64_tr_b16 v[24:25], v216 offset:14048
	s_waitcnt lgkmcnt(2)
	v_mfma_f32_16x16x32_bf16 v[18:21], v[18:21], v[12:15], 0
	s_waitcnt lgkmcnt(0)
	v_mfma_f32_16x16x32_bf16 v[18:21], v[22:25], v[8:11], v[18:21]
	ds_read_b64_tr_b16 v[22:23], v216 offset:18656
	ds_read_b64_tr_b16 v[24:25], v216 offset:23264
	ds_read_b64_tr_b16 v[26:27], v216 offset:27872
	ds_read_b64_tr_b16 v[28:29], v216 offset:32480
	global_store_dwordx2 v211, v[30:31], s[12:13] offset:192
	s_waitcnt lgkmcnt(2)
	v_mfma_f32_16x16x32_bf16 v[18:21], v[22:25], v[0:3], v[18:21]
	s_waitcnt lgkmcnt(0)
	v_mfma_f32_16x16x32_bf16 v[18:21], v[26:29], v[4:7], v[18:21]
	v_lshlrev_b32_e32 v24, 16, v84
	v_and_b32_e32 v22, 0xffff0000, v84
	v_lshlrev_b32_e32 v25, 16, v85
	v_and_b32_e32 v23, 0xffff0000, v85
	s_nop 3
	v_add_f32_e32 v18, v86, v18
	v_add_f32_e32 v19, v86, v19
	v_add_f32_e32 v20, v86, v20
	v_add_f32_e32 v21, v86, v21
	v_mul_f32_e32 v18, v18, v24
	v_mul_f32_e32 v19, v19, v22
	v_mul_f32_e32 v20, v20, v25
	v_mul_f32_e32 v21, v21, v23
	v_cvt_pk_bf16_f32 v30, v18, v19
	v_cvt_pk_bf16_f32 v31, v20, v21
	global_store_dwordx2 v211, v[30:31], s[12:13] offset:224
	s_add_i32 s5, s5, 1
	s_add_i32 s3, s3, -1
	s_cmp_gt_u32 s3, 0
	s_cbranch_scc1 .Lcma_top

.LBB0_890:
	v_readlane_b32 s4, v254, 39
	s_cmpk_lt_u32 s2, 0x80
	v_readlane_b32 s5, v254, 40
	s_cselect_b64 s[0:1], -1, 0
	s_xor_b64 s[4:5], s[4:5], -1
	s_or_b64 s[0:1], s[0:1], s[4:5]
	s_movk_i32 s3, 0x80
	s_and_b64 vcc, exec, s[0:1]
	s_cbranch_vccnz .LBB0_895
	s_cmpk_lt_i32 s2, 0x80
	s_cbranch_scc1 .LBB0_895
	s_mul_i32 s5, s2, 4
	s_add_i32 s5, s5, 256
	s_mov_b32 s3, 4
	s_add_u32 s8, s30, 0x800000
	s_addc_u32 s9, s31, 0
	s_mov_b32 s4, 0x3a800000
	v_readlane_b32 s36, v254, 21
	v_readlane_b32 s37, v254, 22
	v_readlane_b32 s38, v254, 19
	v_readlane_b32 s39, v254, 20
	v_readlane_b32 s40, v254, 25
	v_readlane_b32 s41, v254, 26
	v_readlane_b32 s42, v254, 41
	v_readlane_b32 s43, v254, 42
	v_readlane_b32 s44, v254, 43
	v_readlane_b32 s45, v254, 44
	v_readlane_b32 s96, v254, 45
	v_readlane_b32 s97, v254, 46
	v_and_b32_e32 v1, 15, v195
	v_lshrrev_b32_e32 v0, 4, v195
	v_lshlrev_b32_e32 v2, 4, v1
	v_lshl_add_u32 v200, v0, 11, v2
	v_add_u32_e32 v201, 0x10000, v200
	v_add_u32_e32 v202, 0x20000, v200
	v_add_u32_e32 v203, 0x30000, v200
	v_lshl_add_u32 v204, v0, 8, v2
	v_add_u32_e32 v205, 0x2000, v204
	v_add_u32_e32 v206, 0x4000, v204
	v_add_u32_e32 v207, 0x6000, v204
	v_and_b32_e32 v3, 0x7f, v195
	v_lshlrev_b32_e32 v208, 7, v3
	v_lshlrev_b32_e32 v209, 5, v1
	v_lshrrev_b32_e32 v4, 6, v195
	v_lshl_add_u32 v5, v4, 4, v1
	v_lshlrev_b32_e32 v210, 2, v5
	v_bfe_u32 v6, v195, 4, 2
	v_lshlrev_b32_e32 v7, 3, v6
	v_lshl_add_u32 v211, v5, 11, v7
	v_mul_u32_u24_e32 v8, 0x120, v0
	v_add_u32_e32 v212, v8, v2
	v_mul_u32_u24_e32 v8, 0x110, v0
	v_add_u32_e32 v8, v8, v2
	v_add_u32_e32 v213, 0x9000, v8
	v_lshlrev_b32_e32 v8, 3, v0
	v_add_u32_e32 v214, 0x11800, v8
	v_lshlrev_b32_e32 v8, 3, v195
	v_add_u32_e32 v215, 0x11800, v8
	v_lshrrev_b32_e32 v8, 2, v1
	v_lshl_or_b32 v8, v6, 2, v8
	v_mul_u32_u24_e32 v8, 0x120, v8
	v_and_b32_e32 v9, 3, v195
	v_lshl_add_u32 v216, v9, 3, v8
	v_mul_u32_u24_e32 v8, 0x110, v5
	v_add_u32_e32 v8, v8, v7
	v_add_u32_e32 v217, 0x9000, v8
	s_mov_b32 s0, s5
	s_and_b32 s1, s0, 7
	s_lshr_b32 s0, s0, 3
	s_lshl_b32 s0, s0, 7
	s_lshl_b32 s10, s1, 8
	s_lshl_b32 s11, s0, 11
	s_add_u32 s11, s11, s10
	s_add_u32 s46, s42, s11
	s_addc_u32 s47, s43, 0
	s_add_u32 s6, s96, s11
	s_addc_u32 s7, s97, 0
	s_lshl_b32 s10, s1, 15
	s_add_u32 s48, s8, s10
	s_addc_u32 s49, s9, 0
	s_lshl_b32 s10, s0, 7
	s_add_u32 s50, s44, s10
	s_addc_u32 s51, s45, 0
	s_lshl_b32 s10, s1, 9
	s_add_u32 s14, s36, s10
	s_addc_u32 s15, s37, 0
	s_add_u32 s16, s38, s10
	s_addc_u32 s17, s39, 0
	s_add_u32 s10, s40, s10
	s_addc_u32 s11, s41, 0
	v_readfirstlane_b32 s0, v195
	s_nop 1
	s_cmp_lt_u32 s0, 0x80
	s_cbranch_scc0 .Lcmb_pf0
	global_load_dwordx4 v[132:135], v208, s[50:51]
	global_load_dwordx4 v[136:139], v208, s[50:51] offset:16
	global_load_dwordx4 v[140:143], v208, s[50:51] offset:32
	global_load_dwordx4 v[144:147], v208, s[50:51] offset:48
	global_load_dwordx4 v[148:151], v208, s[50:51] offset:64
	global_load_dwordx4 v[152:155], v208, s[50:51] offset:80
	global_load_dwordx4 v[156:159], v208, s[50:51] offset:96
	global_load_dwordx4 v[160:163], v208, s[50:51] offset:112
